# combo12 + RS_COMMIT done by the leading half (own + partner wave rows) before the align barrier; trailing half skips it; one barrier fewer per IN/UP unit; DPP pair-sum
# baseline (speedup 1.0000x reference)
; #define PG8_WAIT_L(n) asm volatile("s_waitcnt lgkmcnt(" #n ")" ::: "memory")
; #define PG8_BAR __builtin_amdgcn_s_barrier()
; template <class Epi, class Sched, bool ALIGN_EPI = false, bool SP2 = false, bool ACHUNK = false>
; __device__ __forceinline__ void gemm_phase(PG8_LAS unsigned char* lds, const Gemm g, const Sched& S, const Epi& E) {
;     ...
;         if constexpr (ALIGN_EPI) { if (wr == 0) PG8_BAR; }
;         if constexpr (Epi::HAS_RS) {
;             static_assert(ALIGN_EPI, "the extra barrier below assumes the two halves run their epilogues together");
;             PG8_RS_COMMIT(ui & 1); PG8_WAIT_L(0); PG8_BAR;
;             if (has_next) PG8_RS_ISSUE(nxt, (ui + 1) & 1);
.LBB0_110:
	s_waitcnt lgkmcnt(0)
	s_lshl_b32 s4, s76, 10
	s_and_b32 s4, s4, 0x400
	s_mov_b64 s[0:1], exec
	s_and_b64 vcc, exec, s[46:47]
	s_cbranch_vccz .LBB0_112
	v_lshlrev_b32_e32 v36, 4, v222
	v_and_b32_e32 v36, 0x3f0, v36
	v_add_u32_e32 v52, s16, v36
	ds_read_b128 v[36:39], v52
	ds_read_b128 v[40:43], v52 offset:1024
	ds_read_b128 v[44:47], v52 offset:8192
	ds_read_b128 v[48:51], v52 offset:9216
	v_and_b32_e32 v53, 1, v222
	v_lshl_add_u32 v52, v222, 1, s4
	v_add_u32_e32 v52, 0x20400, v52
	s_waitcnt lgkmcnt(0)
	v_add_f32_e32 v36, v36, v37
	v_add_f32_e32 v37, v38, v39
	v_add_f32_e32 v38, v40, v41
	v_add_f32_e32 v39, v42, v43
	v_add_f32_e32 v36, v36, v37
	v_add_f32_e32 v37, v38, v39
	v_add_f32_e32 v36, v36, v37
	v_add_f32_e32 v44, v44, v45
	v_add_f32_e32 v45, v46, v47
	v_add_f32_e32 v46, v48, v49
	v_add_f32_e32 v47, v50, v51
	v_add_f32_e32 v44, v44, v45
	v_add_f32_e32 v45, v46, v47
	v_add_f32_e32 v44, v44, v45
	s_nop 1
	v_add_f32_dpp v36, v36, v36 quad_perm:[1,0,3,2] row_mask:0xf bank_mask:0xf
	v_add_f32_dpp v44, v44, v44 quad_perm:[1,0,3,2] row_mask:0xf bank_mask:0xf
	v_cmp_eq_u32_e32 vcc, 0, v53
	v_fmamk_f32 v36, v36, 0x3a800000, v226
	v_fmamk_f32 v44, v44, 0x3a800000, v226
	v_rsq_f32_e32 v36, v36
	v_rsq_f32_e32 v44, v44
	s_and_saveexec_b64 s[0:1], vcc
	ds_write_b32 v52, v36
	ds_write_b32 v52, v44 offset:512
	s_or_b64 exec, exec, s[0:1]
	s_waitcnt lgkmcnt(0)
	s_barrier
.LBB0_112:
	s_and_b64 vcc, exec, s[40:41]
	s_cbranch_vccnz .LBB0_118
	v_mov_b32_e32 v36, v222
	v_readlane_b32 s0, v254, 60
	v_ashrrev_i32_e32 v2, 1, v36
	s_waitcnt lgkmcnt(0)
	v_ashrrev_i32_e32 v37, 7, v36
	v_lshl_add_u32 v37, s59, 2, v37
	v_lshlrev_b32_e32 v38, 2, v2
	v_bfe_u32 v2, v2, 4, 2
	v_mul_lo_u32 v37, v37, 62
	v_and_or_b32 v2, v38, 60, v2
	v_add3_u32 v2, v2, v37, -2
	v_med3_i32 v2, v2, 0, v229
	v_lshlrev_b32_e32 v2, 6, v2
	v_readlane_b32 s1, v254, 61
	s_mov_b32 m0, s16
	s_nop 0
	v_lshl_add_u64 v[38:39], s[0:1], 0, v[2:3]
	v_lshlrev_b32_e32 v2, 5, v36
	v_and_b32_e32 v2, 32, v2
	v_lshl_add_u64 v[38:39], v[38:39], 0, v[2:3]
	global_load_lds_dwordx4 v[38:39], off
	v_lshl_add_u64 v[38:39], v[38:39], 0, 16
	s_add_i32 m0, s16, 0x400
	s_movk_i32 s0, 0x80
	global_load_lds_dwordx4 v[38:39], off
	v_cmp_gt_i32_e32 vcc, s0, v36
	s_and_saveexec_b64 s[0:1], vcc
	s_cbranch_execz .LBB0_117
	v_ashrrev_i32_e32 v2, 5, v36
	s_movk_i32 s4, 0xb00
	v_mul_lo_u32 v38, v2, s4
	v_ashrrev_i32_e32 v39, 31, v38
	v_cmp_gt_i32_e32 vcc, 3, v2
	v_lshl_add_u64 v[38:39], v[38:39], 2, s[2:3]
	v_mov_b32_e32 v2, s13
	v_cndmask_b32_e32 v39, v2, v39, vcc
	v_mov_b32_e32 v2, s12
	s_lshl_b32 s4, s58, 7
	v_cndmask_b32_e32 v38, v2, v38, vcc
	s_ashr_i32 s5, s4, 31
	v_lshl_add_u64 v[38:39], s[4:5], 2, v[38:39]
	v_lshlrev_b32_e32 v2, 4, v36
	s_lshl_b32 s4, s57, 11
	v_and_b32_e32 v2, 0x1f0, v2
	s_and_b32 s4, s4, 0x800
	v_lshl_add_u64 v[36:37], v[38:39], 0, v[2:3]
	s_add_i32 m0, s55, s4
	s_nop 0
	global_load_lds_dwordx4 v[36:37], off

; #define PG8_WAIT_L(n) asm volatile("s_waitcnt lgkmcnt(" #n ")" ::: "memory")
; #define PG8_BAR __builtin_amdgcn_s_barrier()
; template <class Epi, class Sched, bool ALIGN_EPI = false, bool SP2 = false, bool ACHUNK = false>
; __device__ __forceinline__ void gemm_phase(PG8_LAS unsigned char* lds, const Gemm g, const Sched& S, const Epi& E) {
;     ...
;         if constexpr (ALIGN_EPI) { if (wr == 0) PG8_BAR; }
;         if constexpr (Epi::HAS_RS) {
;             static_assert(ALIGN_EPI, "the extra barrier below assumes the two halves run their epilogues together");
;             PG8_RS_COMMIT(ui & 1); PG8_WAIT_L(0); PG8_BAR;
;             if (has_next) PG8_RS_ISSUE(nxt, (ui + 1) & 1);
.LBB0_379:
	s_waitcnt lgkmcnt(0)
	s_lshl_b32 s6, s47, 10
	s_and_b32 s6, s6, 0x400
	s_mov_b64 s[4:5], exec
	s_and_b64 vcc, exec, s[40:41]
	s_cbranch_vccz .LBB0_381
	v_lshlrev_b32_e32 v146, 4, v141
	v_and_b32_e32 v146, 0x3f0, v146
	v_add_u32_e32 v162, s12, v146
	ds_read_b128 v[146:149], v162
	ds_read_b128 v[150:153], v162 offset:1024
	ds_read_b128 v[154:157], v162 offset:8192
	ds_read_b128 v[158:161], v162 offset:9216
	v_and_b32_e32 v163, 1, v141
	v_lshl_add_u32 v162, v141, 1, s6
	v_add_u32_e32 v162, 0x20400, v162
	s_waitcnt lgkmcnt(0)
	v_add_f32_e32 v146, v146, v147
	v_add_f32_e32 v147, v148, v149
	v_add_f32_e32 v148, v150, v151
	v_add_f32_e32 v149, v152, v153
	v_add_f32_e32 v146, v146, v147
	v_add_f32_e32 v147, v148, v149
	v_add_f32_e32 v146, v146, v147
	v_add_f32_e32 v154, v154, v155
	v_add_f32_e32 v155, v156, v157
	v_add_f32_e32 v156, v158, v159
	v_add_f32_e32 v157, v160, v161
	v_add_f32_e32 v154, v154, v155
	v_add_f32_e32 v155, v156, v157
	v_add_f32_e32 v154, v154, v155
	s_nop 1
	v_add_f32_dpp v146, v146, v146 quad_perm:[1,0,3,2] row_mask:0xf bank_mask:0xf
	v_add_f32_dpp v154, v154, v154 quad_perm:[1,0,3,2] row_mask:0xf bank_mask:0xf
	v_cmp_eq_u32_e32 vcc, 0, v163
	v_fmamk_f32 v146, v146, 0x3a800000, v226
	v_fmamk_f32 v154, v154, 0x3a800000, v226
	v_rsq_f32_e32 v146, v146
	v_rsq_f32_e32 v154, v154
	s_and_saveexec_b64 s[4:5], vcc
	ds_write_b32 v162, v146
	ds_write_b32 v162, v154 offset:512
	s_or_b64 exec, exec, s[4:5]
	s_waitcnt lgkmcnt(0)
	s_barrier
.LBB0_381:
	s_and_b64 vcc, exec, s[38:39]
	s_cbranch_vccnz .LBB0_387
	v_mov_b32_e32 v146, v141
	v_readlane_b32 s4, v254, 58
	v_ashrrev_i32_e32 v2, 1, v146
	v_lshl_add_u32 v148, s45, 8, v2
	v_ashrrev_i32_e32 v149, 31, v148
	v_lshlrev_b64 v[148:149], 6, v[148:149]
	v_readlane_b32 s5, v254, 59
	s_waitcnt lgkmcnt(0)
	v_lshlrev_b32_e32 v147, 5, v146
	v_and_b32_e32 v2, 32, v147
	v_lshl_add_u64 v[148:149], s[4:5], 0, v[148:149]
	s_mov_b32 m0, s12
	v_lshl_add_u64 v[148:149], v[148:149], 0, v[2:3]
	global_load_lds_dwordx4 v[148:149], off
	v_lshl_add_u64 v[148:149], v[148:149], 0, 16
	s_add_i32 m0, s12, 0x400
	s_cmp_gt_i32 s33, 9
	global_load_lds_dwordx4 v[148:149], off
	s_cselect_b32 s4, 64, 0
	v_cmp_gt_i32_e32 vcc, s4, v146
	s_and_saveexec_b64 s[4:5], vcc
	s_cbranch_execz .LBB0_386
	v_and_b32_e32 v148, 0xfffffc00, v147
	s_lshl_b32 s6, s33, 7
	v_ashrrev_i32_e32 v149, 31, v148
	s_addk_i32 s6, 0xfb00
	v_lshl_add_u64 v[148:149], v[148:149], 2, s[2:3]
	s_ashr_i32 s7, s6, 31
	v_lshl_add_u64 v[148:149], s[6:7], 2, v[148:149]
	v_lshlrev_b32_e32 v2, 4, v146
	s_lshl_b32 s6, s44, 11
	v_and_b32_e32 v2, 0x1f0, v2
	s_and_b32 s6, s6, 0x800
	v_lshl_add_u64 v[146:147], v[148:149], 0, v[2:3]
	s_add_i32 m0, s36, s6
	s_nop 0
	global_load_lds_dwordx4 v[146:147], off
